# v3: indexer key chunks loaded once per workgroup and shared through LDS (plus OUT stats atomics pre-reduced in LDS)
# speedup vs baseline: 1.0238x; 1.0238x over previous
.LBB0_105:
	s_lshl_b32 s1, s21, 4
	s_and_b32 s2, s1, 0x7f0
	s_and_b32 s0, s21, 0x100
	s_xor_b32 s6, s2, 0x7f0
	s_cmp_eq_u32 s0, 0
	s_cselect_b32 s2, s2, s6
	s_add_i32 s10, s2, s17
	s_and_b32 s33, s1, 0xfffff800
	s_add_i32 s6, s10, s33
	v_or_b32_e32 v2, s6, v249
	v_ashrrev_i32_e32 v3, 31, v2
	v_lshlrev_b64 v[2:3], 11, v[2:3]
	s_ashr_i32 s7, s6, 31
	v_lshl_add_u64 v[2:3], v[232:233], 0, v[2:3]
	s_lshl_b64 s[0:1], s[6:7], 6
	global_load_dwordx4 v[34:37], v[2:3], off
	global_load_dwordx4 v[38:41], v[2:3], off offset:32
	global_load_dwordx4 v[42:45], v[2:3], off offset:64
	global_load_dwordx4 v[46:49], v[2:3], off offset:96
	v_lshl_add_u64 v[2:3], v[238:239], 0, s[0:1]
	v_writelane_b32 v254, s6, 35
	s_or_b32 s0, s6, 1
	s_ashr_i32 s1, s0, 31
	s_lshl_b64 s[0:1], s[0:1], 6
	global_load_dwordx4 v[50:53], v[2:3], off
	global_load_dwordx4 v[54:57], v[2:3], off offset:32
	v_lshl_add_u64 v[2:3], v[238:239], 0, s[0:1]
	global_load_dwordx4 v[58:61], v[2:3], off
	global_load_dwordx4 v[62:65], v[2:3], off offset:32
	s_lshr_b32 s0, s2, 5
	s_add_i32 s0, s0, 2
	v_or_b32_e32 v2, s33, v248
	s_lshr_b32 s8, s0, 1
	v_ashrrev_i32_e32 v3, 31, v2
	s_add_i32 s9, s8, -1
	v_lshlrev_b64 v[2:3], 7, v[2:3]
	s_cmp_gt_u32 s2, 48
	v_lshl_add_u64 v[240:241], v[234:235], 0, v[2:3]
	s_cselect_b32 s2, 0x2000, 0
	v_lshl_add_u64 v[2:3], v[240:241], 0, s[2:3]
	s_movk_i32 s0, 0x1000
	v_add_co_u32_e32 v4, vcc, s0, v2
	v_writelane_b32 v254, s7, 36
	s_nop 0
	v_addc_co_u32_e32 v5, vcc, 0, v3, vcc
	v_add_co_u32_e32 v6, vcc, 0x1000, v240
	s_mov_b32 s2, 4
	s_nop 0
	v_addc_co_u32_e32 v7, vcc, 0, v241, vcc
	v_mov_b32_e32 v251, v250
	v_mov_b32_e32 v0, v245
	s_waitcnt vmcnt(0)
	s_waitcnt vmcnt(6)
	s_waitcnt vmcnt(5)
	s_waitcnt vmcnt(4)
	s_waitcnt vmcnt(3)
	s_waitcnt vmcnt(2)
	s_waitcnt vmcnt(1)
	s_waitcnt vmcnt(0)
	v_readlane_b32 s0, v253, 23
	s_lshl_b32 s1, s33, 7
	s_nop 3
	s_lshl_b32 s0, s0, 10
	v_lshl_add_u32 v74, v178, 4, s0
	s_add_u32 s6, s22, 0x32600000
	s_addc_u32 s7, s23, 0
	s_add_u32 s6, s6, s1
	s_addc_u32 s7, s7, 0
	v_mov_b32_e32 v75, 0
	v_lshl_add_u64 v[70:71], s[6:7], 0, v[74:75]
	s_movk_i32 s12, 0x90
	v_lshrrev_b32_e32 v76, 7, v74
	v_and_b32_e32 v77, 0x70, v74
	v_mad_u32_u24 v72, v76, s12, v77
	v_add_u32_e32 v72, 0x20200, v72
	v_lshrrev_b32_e32 v76, 5, v178
	v_lshlrev_b32_e32 v76, 4, v76
	v_mad_u32_u24 v73, v248, s12, v76
	v_add_u32_e32 v73, 0x20200, v73
	s_mov_b32 s12, 0x2000
	s_mov_b32 s13, 0
	global_load_dwordx4 v[66:69], v[70:71], off
	v_lshl_add_u64 v[70:71], v[70:71], 0, s[12:13]
	s_mov_b32 s2, 0
	s_mov_b32 s11, 0
	s_waitcnt vmcnt(0)
	ds_write_b128 v72, v[66:69]
	s_waitcnt lgkmcnt(0)
	s_cmp_lt_u32 s8, 2
	s_cbranch_scc1 .Lidx_pro1
	global_load_dwordx4 v[66:69], v[70:71], off
	v_lshl_add_u64 v[70:71], v[70:71], 0, s[12:13]
.Lidx_pro1:
	s_barrier
.Lidx_loop:
	v_add_u32_e32 v76, s11, v73
	ds_read_b128 v[118:121], v76
	ds_read_b128 v[126:129], v76 offset:4608
	ds_read_b128 v[114:117], v76 offset:32
	ds_read_b128 v[122:125], v76 offset:4640
	ds_read_b128 v[110:113], v76 offset:64
	ds_read_b128 v[106:109], v76 offset:4672
	ds_read_b128 v[86:89], v76 offset:4704
	ds_read_b128 v[102:105], v76 offset:96
	s_waitcnt lgkmcnt(6)
	v_mfma_f32_32x32x16_bf16 v[18:33], v[34:37], v[118:121], 0
	v_mfma_f32_32x32x16_bf16 v[2:17], v[34:37], v[126:129], 0
	s_waitcnt lgkmcnt(4)
	v_mfma_f32_32x32x16_bf16 v[18:33], v[38:41], v[114:117], v[18:33]
	v_mfma_f32_32x32x16_bf16 v[2:17], v[38:41], v[122:125], v[2:17]
	s_waitcnt lgkmcnt(2)
	v_mfma_f32_32x32x16_bf16 v[18:33], v[42:45], v[110:113], v[18:33]
	v_mfma_f32_32x32x16_bf16 v[2:17], v[42:45], v[106:109], v[2:17]
	s_waitcnt lgkmcnt(0)
	v_mfma_f32_32x32x16_bf16 v[2:17], v[46:49], v[86:89], v[2:17]
	v_mfma_f32_32x32x16_bf16 v[18:33], v[46:49], v[102:105], v[18:33]
	s_nop 10
	v_max_i32_e32 v2, 0, v2
	v_fma_f32 v2, v50, v2, 0
	v_max_i32_e32 v10, 0, v10
	v_max_i32_e32 v3, 0, v3
	v_fma_f32 v10, v58, v10, 0
	v_fmac_f32_e32 v2, v51, v3
	v_max_i32_e32 v3, 0, v11
	v_max_i32_e32 v18, 0, v18
	v_fma_f32 v18, v50, v18, 0
	v_max_i32_e32 v26, 0, v26
	v_max_i32_e32 v19, 0, v19
	v_fma_f32 v26, v58, v26, 0
	v_fmac_f32_e32 v18, v51, v19
	v_max_i32_e32 v19, 0, v27
	v_fmac_f32_e32 v10, v59, v3
	v_max_i32_e32 v3, 0, v20
	v_fmac_f32_e32 v26, v59, v19
	v_fmac_f32_e32 v18, v52, v3
	v_max_i32_e32 v3, 0, v28
	v_fmac_f32_e32 v26, v60, v3
	v_max_i32_e32 v3, 0, v4
	v_fmac_f32_e32 v2, v52, v3
	v_max_i32_e32 v3, 0, v12
	v_fmac_f32_e32 v10, v60, v3
	v_max_i32_e32 v3, 0, v21
	v_fmac_f32_e32 v18, v53, v3
	v_max_i32_e32 v3, 0, v29
	v_fmac_f32_e32 v26, v61, v3
	v_max_i32_e32 v3, 0, v5
	v_fmac_f32_e32 v2, v53, v3
	v_max_i32_e32 v3, 0, v13
	v_fmac_f32_e32 v10, v61, v3
	v_max_i32_e32 v3, 0, v22
	v_fmac_f32_e32 v18, v54, v3
	v_max_i32_e32 v3, 0, v30
	v_fmac_f32_e32 v26, v62, v3
	v_max_i32_e32 v3, 0, v6
	v_fmac_f32_e32 v2, v54, v3
	v_max_i32_e32 v3, 0, v14
	v_fmac_f32_e32 v10, v62, v3
	v_max_i32_e32 v3, 0, v23
	v_fmac_f32_e32 v18, v55, v3
	v_max_i32_e32 v3, 0, v31
	v_fmac_f32_e32 v26, v63, v3
	v_max_i32_e32 v3, 0, v7
	v_fmac_f32_e32 v2, v55, v3
	v_max_i32_e32 v3, 0, v15
	v_fmac_f32_e32 v10, v63, v3
	v_max_i32_e32 v3, 0, v24
	v_fmac_f32_e32 v18, v56, v3
	v_max_i32_e32 v3, 0, v32
	v_fmac_f32_e32 v26, v64, v3
	v_max_i32_e32 v3, 0, v8
	v_fmac_f32_e32 v2, v56, v3
	v_max_i32_e32 v3, 0, v16
	v_fmac_f32_e32 v10, v64, v3
	v_max_i32_e32 v3, 0, v25
	v_fmac_f32_e32 v18, v57, v3
	v_max_i32_e32 v3, 0, v33
	v_fmac_f32_e32 v26, v65, v3
	v_max_i32_e32 v3, 0, v9
	v_fmac_f32_e32 v2, v57, v3
	v_max_i32_e32 v3, 0, v17
	v_fmac_f32_e32 v10, v65, v3
	v_mov_b32_e32 v3, v18
	v_mov_b32_e32 v5, v26
	v_mov_b32_e32 v4, v2
	v_mov_b32_e32 v6, v10
	v_permlane32_swap_b32_e32 v18, v3
	v_permlane32_swap_b32_e32 v26, v5
	v_permlane32_swap_b32_e32 v2, v4
	v_permlane32_swap_b32_e32 v10, v6
	s_and_saveexec_b64 s[6:7], s[4:5]
	s_xor_b64 s[6:7], exec, s[6:7]
	v_add_f32_e32 v2, v10, v6
	v_add_f32_e32 v3, v26, v5
	ds_write2_b32 v0, v3, v2 offset1:32
	s_andn2_saveexec_b64 s[6:7], s[6:7]
	v_add_f32_e32 v2, v2, v4
	v_add_f32_e32 v3, v18, v3
	ds_write2_b32 v251, v3, v2 offset1:32
	s_or_b64 exec, exec, s[6:7]
	v_add_u32_e32 v0, 0x100, v0
	v_add_u32_e32 v251, 0x100, v251
	s_add_i32 s2, s2, 1
	s_cmp_ge_u32 s2, s8
	s_cbranch_scc1 .Lidx_done
	s_xor_b32 s11, s11, 0x2400
	s_waitcnt vmcnt(0)
	v_add_u32_e32 v76, s11, v72
	ds_write_b128 v76, v[66:69]
	s_waitcnt lgkmcnt(0)
	s_add_i32 s0, s2, 1
	s_cmp_ge_u32 s0, s8
	s_cbranch_scc1 .Lidx_nold
	global_load_dwordx4 v[66:69], v[70:71], off
	v_lshl_add_u64 v[70:71], v[70:71], 0, s[12:13]
.Lidx_nold:
	s_barrier
	s_branch .Lidx_loop
.Lidx_done:
	s_waitcnt lgkmcnt(0)
	s_barrier

	.amdhsa_kernel _Z14fwd_megakernel4Args
		.amdhsa_group_segment_fixed_size 16384
		.amdhsa_private_segment_fixed_size 0
		.amdhsa_kernarg_size 376
		.amdhsa_user_sgpr_count 2
		.amdhsa_user_sgpr_dispatch_ptr 0
		.amdhsa_user_sgpr_queue_ptr 0
		.amdhsa_user_sgpr_kernarg_segment_ptr 1
		.amdhsa_user_sgpr_dispatch_id 0
		.amdhsa_user_sgpr_kernarg_preload_length 0
		.amdhsa_user_sgpr_kernarg_preload_offset 0
		.amdhsa_user_sgpr_private_segment_size 0
		.amdhsa_uses_dynamic_stack 0
		.amdhsa_enable_private_segment 0
		.amdhsa_system_sgpr_workgroup_id_x 1
		.amdhsa_system_sgpr_workgroup_id_y 0
		.amdhsa_system_sgpr_workgroup_id_z 0
		.amdhsa_system_sgpr_workgroup_info 0
		.amdhsa_system_vgpr_workitem_id 2
		.amdhsa_next_free_vgpr 256
		.amdhsa_next_free_sgpr 102
		.amdhsa_accum_offset 256
		.amdhsa_reserve_vcc 1
		.amdhsa_float_round_mode_32 0
		.amdhsa_float_round_mode_16_64 0
		.amdhsa_float_denorm_mode_32 3
		.amdhsa_float_denorm_mode_16_64 3
		.amdhsa_dx10_clamp 1
		.amdhsa_ieee_mode 1
		.amdhsa_fp16_overflow 0
		.amdhsa_tg_split 0
		.amdhsa_exception_fp_ieee_invalid_op 0
		.amdhsa_exception_fp_denorm_src 0
		.amdhsa_exception_fp_ieee_div_zero 0
		.amdhsa_exception_fp_ieee_overflow 0
		.amdhsa_exception_fp_ieee_underflow 0
		.amdhsa_exception_fp_ieee_inexact 0
		.amdhsa_exception_int_div_zero 0
	.end_amdhsa_kernel

amdhsa.kernels:
  - .agpr_count:     0
    .args:
      - .offset:         0
        .size:           120
        .value_kind:     by_value
      - .offset:         120
        .size:           4
        .value_kind:     hidden_block_count_x
      - .offset:         124
        .size:           4
        .value_kind:     hidden_block_count_y
      - .offset:         128
        .size:           4
        .value_kind:     hidden_block_count_z
      - .offset:         132
        .size:           2
        .value_kind:     hidden_group_size_x
      - .offset:         134
        .size:           2
        .value_kind:     hidden_group_size_y
      - .offset:         136
        .size:           2
        .value_kind:     hidden_group_size_z
      - .offset:         138
        .size:           2
        .value_kind:     hidden_remainder_x
      - .offset:         140
        .size:           2
        .value_kind:     hidden_remainder_y
      - .offset:         142
        .size:           2
        .value_kind:     hidden_remainder_z
      - .offset:         160
        .size:           8
        .value_kind:     hidden_global_offset_x
      - .offset:         168
        .size:           8
        .value_kind:     hidden_global_offset_y
      - .offset:         176
        .size:           8
        .value_kind:     hidden_global_offset_z
      - .offset:         184
        .size:           2
        .value_kind:     hidden_grid_dims
      - .offset:         208
        .size:           8
        .value_kind:     hidden_multigrid_sync_arg
      - .offset:         240
        .size:           4
        .value_kind:     hidden_dynamic_lds_size
    .group_segment_fixed_size: 16384
    .kernarg_segment_align: 8
    .kernarg_segment_size: 376
    .language:       OpenCL C
    .language_version:
      - 2
      - 0
    .max_flat_workgroup_size: 512
    .name:           _Z14fwd_megakernel4Args
    .private_segment_fixed_size: 0
    .sgpr_count:     108
    .sgpr_spill_count: 286
    .symbol:         _Z14fwd_megakernel4Args.kd
    .uniform_work_group_size: 1
    .uses_dynamic_stack: false
    .vgpr_count:     256
    .vgpr_spill_count: 0
    .wavefront_size: 64
